# early barrier moved above last 8 MFMAs (was 4) in the 4 GEMM K-loops, rest as shared-score version
# baseline (speedup 1.0000x reference)
.LBB0_262:
	s_add_u32 s2, s0, 0xfff80080
	s_addc_u32 s3, s1, -1
	s_add_i32 s6, 0, 0x10000
	s_cmp_eq_u32 s48, 28
	s_cselect_b32 s9, s25, s3
	s_cselect_b32 s8, s33, s2
	s_cselect_b32 s5, s39, s47
	s_cselect_b32 s4, s41, s46
	s_add_i32 s7, 0, 0x14000
	v_add_u32_e32 v174, s6, v10
	v_add_u32_e32 v190, s7, v10
	ds_read_b128 v[146:149], v174
	ds_read_b128 v[166:169], v174 offset:1024
	ds_read_b128 v[170:173], v174 offset:2048
	ds_read_b128 v[174:177], v174 offset:3072
	ds_read_b128 v[178:181], v190
	ds_read_b128 v[182:185], v190 offset:1024
	ds_read_b128 v[186:189], v190 offset:2048
	ds_read_b128 v[190:193], v190 offset:3072
	v_lshl_add_u64 v[212:213], s[0:1], 0, v[142:143]
	s_add_i32 m0, s15, 0xc000
	ds_read_b128 v[194:197], v161
	ds_read_b128 v[198:201], v161 offset:1024
	ds_read_b128 v[202:205], v161 offset:2048
	ds_read_b128 v[228:231], v161 offset:3072
	ds_read_b128 v[232:235], v161 offset:4096
	ds_read_b128 v[236:239], v161 offset:5120
	ds_read_b128 v[240:243], v161 offset:6144
	ds_read_b128 v[244:247], v161 offset:7168
	global_load_lds_dwordx4 v[212:213], off
	v_lshl_add_u64 v[212:213], s[0:1], 0, v[144:145]
	s_add_i32 m0, s15, 0xe000
	s_nop 0
	global_load_lds_dwordx4 v[212:213], off
	s_waitcnt vmcnt(8)
	s_waitcnt lgkmcnt(0)
	s_barrier
	s_setprio 1
	s_waitcnt lgkmcnt(0)
	v_mfma_f32_16x16x32_bf16 v[128:131], v[146:149], v[194:197], v[128:131]
	v_mfma_f32_16x16x32_bf16 v[128:131], v[166:169], v[198:201], v[128:131]
	v_mfma_f32_16x16x32_bf16 v[124:127], v[170:173], v[194:197], v[124:127]
	v_mfma_f32_16x16x32_bf16 v[124:127], v[174:177], v[198:201], v[124:127]
	v_mfma_f32_16x16x32_bf16 v[112:115], v[146:149], v[202:205], v[112:115]
	v_mfma_f32_16x16x32_bf16 v[112:115], v[166:169], v[228:231], v[112:115]
	v_mfma_f32_16x16x32_bf16 v[108:111], v[170:173], v[202:205], v[108:111]
	v_mfma_f32_16x16x32_bf16 v[108:111], v[174:177], v[228:231], v[108:111]
	v_mfma_f32_16x16x32_bf16 v[96:99], v[146:149], v[232:235], v[96:99]
	v_mfma_f32_16x16x32_bf16 v[96:99], v[166:169], v[236:239], v[96:99]
	v_mfma_f32_16x16x32_bf16 v[92:95], v[170:173], v[232:235], v[92:95]
	v_mfma_f32_16x16x32_bf16 v[92:95], v[174:177], v[236:239], v[92:95]
	v_mfma_f32_16x16x32_bf16 v[80:83], v[146:149], v[240:243], v[80:83]
	v_mfma_f32_16x16x32_bf16 v[80:83], v[166:169], v[244:247], v[80:83]
	v_mfma_f32_16x16x32_bf16 v[76:79], v[170:173], v[240:243], v[76:79]
	v_mfma_f32_16x16x32_bf16 v[76:79], v[174:177], v[244:247], v[76:79]
	s_setprio 0
	s_setprio 1
	v_mfma_f32_16x16x32_bf16 v[120:123], v[178:181], v[194:197], v[120:123]
	v_mfma_f32_16x16x32_bf16 v[120:123], v[182:185], v[198:201], v[120:123]
	v_mfma_f32_16x16x32_bf16 v[116:119], v[186:189], v[194:197], v[116:119]
	v_mfma_f32_16x16x32_bf16 v[116:119], v[190:193], v[198:201], v[116:119]
	v_mfma_f32_16x16x32_bf16 v[104:107], v[178:181], v[202:205], v[104:107]
	v_mfma_f32_16x16x32_bf16 v[104:107], v[182:185], v[228:231], v[104:107]
	v_mfma_f32_16x16x32_bf16 v[100:103], v[186:189], v[202:205], v[100:103]
	v_mfma_f32_16x16x32_bf16 v[100:103], v[190:193], v[228:231], v[100:103]
	s_setprio 2
	s_barrier
	v_mfma_f32_16x16x32_bf16 v[88:91], v[178:181], v[232:235], v[88:91]
	v_mfma_f32_16x16x32_bf16 v[88:91], v[182:185], v[236:239], v[88:91]
	v_mfma_f32_16x16x32_bf16 v[84:87], v[186:189], v[232:235], v[84:87]
	v_mfma_f32_16x16x32_bf16 v[84:87], v[190:193], v[236:239], v[84:87]
	v_mfma_f32_16x16x32_bf16 v[72:75], v[178:181], v[240:243], v[72:75]
	v_mfma_f32_16x16x32_bf16 v[72:75], v[182:185], v[244:247], v[72:75]
	v_mfma_f32_16x16x32_bf16 v[68:71], v[186:189], v[240:243], v[68:71]
	v_mfma_f32_16x16x32_bf16 v[68:71], v[190:193], v[244:247], v[68:71]
	s_setprio 0
	s_add_i32 s2, s6, s14
	v_lshl_add_u64 v[212:213], s[4:5], 0, v[136:137]
	s_mov_b32 m0, s2
	ds_read_b128 v[194:197], v161 offset:16384
	ds_read_b128 v[198:201], v161 offset:17408
	ds_read_b128 v[202:205], v161 offset:18432
	ds_read_b128 v[228:231], v161 offset:19456
	ds_read_b128 v[232:235], v161 offset:20480
	ds_read_b128 v[236:239], v161 offset:21504
	ds_read_b128 v[240:243], v161 offset:22528
	ds_read_b128 v[244:247], v161 offset:23552
	global_load_lds_dwordx4 v[212:213], off
	s_add_i32 m0, s2, 0x2000
	s_add_u32 s2, s4, 0x80000
	v_lshl_add_u64 v[214:215], s[4:5], 0, v[132:133]
	s_addc_u32 s3, s5, 0
	s_add_i32 s6, s7, s14
	global_load_lds_dwordx4 v[214:215], off
	v_lshl_add_u64 v[248:249], s[2:3], 0, v[136:137]
	s_mov_b32 m0, s6
	v_lshl_add_u64 v[216:217], s[8:9], 0, v[134:135]
	global_load_lds_dwordx4 v[248:249], off
	v_lshl_add_u64 v[248:249], s[2:3], 0, v[132:133]
	s_add_i32 m0, s6, 0x2000
	s_nop 0
	global_load_lds_dwordx4 v[248:249], off
	v_lshl_add_u64 v[248:249], s[8:9], 0, v[138:139]
	s_mov_b32 m0, s15
	s_nop 0
	global_load_lds_dwordx4 v[248:249], off
	s_mov_b32 m0, s18
	s_nop 0
	global_load_lds_dwordx4 v[216:217], off
	s_waitcnt vmcnt(8)
	s_waitcnt lgkmcnt(0)
	s_barrier
	s_setprio 1
	s_waitcnt lgkmcnt(0)
	v_mfma_f32_16x16x32_bf16 v[64:67], v[146:149], v[194:197], v[64:67]
	v_mfma_f32_16x16x32_bf16 v[64:67], v[166:169], v[198:201], v[64:67]
	v_mfma_f32_16x16x32_bf16 v[60:63], v[170:173], v[194:197], v[60:63]
	v_mfma_f32_16x16x32_bf16 v[60:63], v[174:177], v[198:201], v[60:63]
	v_mfma_f32_16x16x32_bf16 v[48:51], v[146:149], v[202:205], v[48:51]
	v_mfma_f32_16x16x32_bf16 v[48:51], v[166:169], v[228:231], v[48:51]
	v_mfma_f32_16x16x32_bf16 v[44:47], v[170:173], v[202:205], v[44:47]
	v_mfma_f32_16x16x32_bf16 v[44:47], v[174:177], v[228:231], v[44:47]
	v_mfma_f32_16x16x32_bf16 v[32:35], v[146:149], v[232:235], v[32:35]
	v_mfma_f32_16x16x32_bf16 v[32:35], v[166:169], v[236:239], v[32:35]
	v_mfma_f32_16x16x32_bf16 v[28:31], v[170:173], v[232:235], v[28:31]
	v_mfma_f32_16x16x32_bf16 v[28:31], v[174:177], v[236:239], v[28:31]
	v_mfma_f32_16x16x32_bf16 v[16:19], v[146:149], v[240:243], v[16:19]
	v_mfma_f32_16x16x32_bf16 v[16:19], v[166:169], v[244:247], v[16:19]
	v_mfma_f32_16x16x32_bf16 v[12:15], v[170:173], v[240:243], v[12:15]
	v_mfma_f32_16x16x32_bf16 v[12:15], v[174:177], v[244:247], v[12:15]
	s_setprio 0
	s_setprio 1
	v_mfma_f32_16x16x32_bf16 v[56:59], v[178:181], v[194:197], v[56:59]
	v_mfma_f32_16x16x32_bf16 v[56:59], v[182:185], v[198:201], v[56:59]
	v_mfma_f32_16x16x32_bf16 v[52:55], v[186:189], v[194:197], v[52:55]
	v_mfma_f32_16x16x32_bf16 v[52:55], v[190:193], v[198:201], v[52:55]
	v_mfma_f32_16x16x32_bf16 v[40:43], v[178:181], v[202:205], v[40:43]
	v_mfma_f32_16x16x32_bf16 v[40:43], v[182:185], v[228:231], v[40:43]
	v_mfma_f32_16x16x32_bf16 v[36:39], v[186:189], v[202:205], v[36:39]
	v_mfma_f32_16x16x32_bf16 v[36:39], v[190:193], v[228:231], v[36:39]
	s_setprio 2
	s_barrier
	v_mfma_f32_16x16x32_bf16 v[24:27], v[178:181], v[232:235], v[24:27]
	v_mfma_f32_16x16x32_bf16 v[24:27], v[182:185], v[236:239], v[24:27]
	v_mfma_f32_16x16x32_bf16 v[20:23], v[186:189], v[232:235], v[20:23]
	v_mfma_f32_16x16x32_bf16 v[20:23], v[190:193], v[236:239], v[20:23]
	v_mfma_f32_16x16x32_bf16 v[6:9], v[178:181], v[240:243], v[6:9]
	v_mfma_f32_16x16x32_bf16 v[6:9], v[182:185], v[244:247], v[6:9]
	v_mfma_f32_16x16x32_bf16 v[2:5], v[186:189], v[240:243], v[2:5]
	v_mfma_f32_16x16x32_bf16 v[2:5], v[190:193], v[244:247], v[2:5]
	s_setprio 0
	s_add_i32 s6, 0, 0x18000
	s_add_i32 s7, 0, 0x1c000
	v_add_u32_e32 v174, s6, v10
	v_add_u32_e32 v190, s7, v10
	ds_read_b128 v[146:149], v174
	ds_read_b128 v[166:169], v174 offset:1024
	ds_read_b128 v[170:173], v174 offset:2048
	ds_read_b128 v[174:177], v174 offset:3072
	ds_read_b128 v[178:181], v190
	ds_read_b128 v[182:185], v190 offset:1024
	ds_read_b128 v[186:189], v190 offset:2048
	ds_read_b128 v[190:193], v190 offset:3072
	s_add_u32 s2, s8, 0x80000
	s_addc_u32 s3, s9, 0
	s_mov_b32 m0, s19
	v_lshl_add_u64 v[218:219], s[2:3], 0, v[138:139]
	ds_read_b128 v[194:197], v161 offset:32768
	ds_read_b128 v[198:201], v161 offset:33792
	ds_read_b128 v[202:205], v161 offset:34816
	ds_read_b128 v[228:231], v161 offset:35840
	ds_read_b128 v[232:235], v161 offset:36864
	ds_read_b128 v[236:239], v161 offset:37888
	ds_read_b128 v[240:243], v161 offset:38912
	ds_read_b128 v[244:247], v161 offset:39936
	global_load_lds_dwordx4 v[218:219], off
	v_lshl_add_u64 v[218:219], s[2:3], 0, v[134:135]
	s_mov_b32 m0, s30
	s_nop 0
	global_load_lds_dwordx4 v[218:219], off
	s_waitcnt vmcnt(8)
	s_waitcnt lgkmcnt(0)
	s_barrier
	s_setprio 1
	s_waitcnt lgkmcnt(0)
	v_mfma_f32_16x16x32_bf16 v[128:131], v[146:149], v[194:197], v[128:131]
	v_mfma_f32_16x16x32_bf16 v[128:131], v[166:169], v[198:201], v[128:131]
	v_mfma_f32_16x16x32_bf16 v[124:127], v[170:173], v[194:197], v[124:127]
	v_mfma_f32_16x16x32_bf16 v[124:127], v[174:177], v[198:201], v[124:127]
	v_mfma_f32_16x16x32_bf16 v[112:115], v[146:149], v[202:205], v[112:115]
	v_mfma_f32_16x16x32_bf16 v[112:115], v[166:169], v[228:231], v[112:115]
	v_mfma_f32_16x16x32_bf16 v[108:111], v[170:173], v[202:205], v[108:111]
	v_mfma_f32_16x16x32_bf16 v[108:111], v[174:177], v[228:231], v[108:111]
	v_mfma_f32_16x16x32_bf16 v[96:99], v[146:149], v[232:235], v[96:99]
	v_mfma_f32_16x16x32_bf16 v[96:99], v[166:169], v[236:239], v[96:99]
	v_mfma_f32_16x16x32_bf16 v[92:95], v[170:173], v[232:235], v[92:95]
	v_mfma_f32_16x16x32_bf16 v[92:95], v[174:177], v[236:239], v[92:95]
	v_mfma_f32_16x16x32_bf16 v[80:83], v[146:149], v[240:243], v[80:83]
	v_mfma_f32_16x16x32_bf16 v[80:83], v[166:169], v[244:247], v[80:83]
	v_mfma_f32_16x16x32_bf16 v[76:79], v[170:173], v[240:243], v[76:79]
	v_mfma_f32_16x16x32_bf16 v[76:79], v[174:177], v[244:247], v[76:79]
	s_setprio 0
	s_setprio 1
	v_mfma_f32_16x16x32_bf16 v[120:123], v[178:181], v[194:197], v[120:123]
	v_mfma_f32_16x16x32_bf16 v[120:123], v[182:185], v[198:201], v[120:123]
	v_mfma_f32_16x16x32_bf16 v[116:119], v[186:189], v[194:197], v[116:119]
	v_mfma_f32_16x16x32_bf16 v[116:119], v[190:193], v[198:201], v[116:119]
	v_mfma_f32_16x16x32_bf16 v[104:107], v[178:181], v[202:205], v[104:107]
	v_mfma_f32_16x16x32_bf16 v[104:107], v[182:185], v[228:231], v[104:107]
	v_mfma_f32_16x16x32_bf16 v[100:103], v[186:189], v[202:205], v[100:103]
	v_mfma_f32_16x16x32_bf16 v[100:103], v[190:193], v[228:231], v[100:103]
	s_setprio 2
	s_barrier
	v_mfma_f32_16x16x32_bf16 v[88:91], v[178:181], v[232:235], v[88:91]
	v_mfma_f32_16x16x32_bf16 v[88:91], v[182:185], v[236:239], v[88:91]
	v_mfma_f32_16x16x32_bf16 v[84:87], v[186:189], v[232:235], v[84:87]
	v_mfma_f32_16x16x32_bf16 v[84:87], v[190:193], v[236:239], v[84:87]
	v_mfma_f32_16x16x32_bf16 v[72:75], v[178:181], v[240:243], v[72:75]
	v_mfma_f32_16x16x32_bf16 v[72:75], v[182:185], v[244:247], v[72:75]
	v_mfma_f32_16x16x32_bf16 v[68:71], v[186:189], v[240:243], v[68:71]
	v_mfma_f32_16x16x32_bf16 v[68:71], v[190:193], v[244:247], v[68:71]
	s_setprio 0
	s_add_i32 s2, s6, s14
	v_lshl_add_u64 v[212:213], v[212:213], 0, s[86:87]
	s_mov_b32 m0, s2
	ds_read_b128 v[194:197], v161 offset:49152
	ds_read_b128 v[198:201], v161 offset:50176
	ds_read_b128 v[202:205], v161 offset:51200
	ds_read_b128 v[228:231], v161 offset:52224
	ds_read_b128 v[232:235], v161 offset:53248
	ds_read_b128 v[236:239], v161 offset:54272
	ds_read_b128 v[240:243], v161 offset:55296
	ds_read_b128 v[244:247], v161 offset:56320
	global_load_lds_dwordx4 v[212:213], off
	s_add_i32 m0, s2, 0x2000
	s_add_u32 s2, s4, 0x80080
	v_lshl_add_u64 v[212:213], v[214:215], 0, s[86:87]
	s_addc_u32 s3, s5, 0
	s_add_i32 s4, s7, s14
	global_load_lds_dwordx4 v[212:213], off
	v_lshl_add_u64 v[212:213], s[2:3], 0, v[136:137]
	s_mov_b32 m0, s4
	s_nop 0
	global_load_lds_dwordx4 v[212:213], off
	v_lshl_add_u64 v[212:213], s[2:3], 0, v[132:133]
	s_add_i32 m0, s4, 0x2000
	s_nop 0
	global_load_lds_dwordx4 v[212:213], off
	v_lshl_add_u64 v[212:213], v[248:249], 0, s[86:87]
	s_mov_b32 m0, s31
	s_nop 0
	global_load_lds_dwordx4 v[212:213], off
	v_lshl_add_u64 v[212:213], v[216:217], 0, s[86:87]
	s_mov_b32 m0, s34
	s_nop 0
	global_load_lds_dwordx4 v[212:213], off
	s_waitcnt vmcnt(8)
	s_waitcnt lgkmcnt(0)
	s_barrier
	s_setprio 1
	s_waitcnt lgkmcnt(0)
	v_mfma_f32_16x16x32_bf16 v[64:67], v[146:149], v[194:197], v[64:67]
	v_mfma_f32_16x16x32_bf16 v[64:67], v[166:169], v[198:201], v[64:67]
	v_mfma_f32_16x16x32_bf16 v[60:63], v[170:173], v[194:197], v[60:63]
	v_mfma_f32_16x16x32_bf16 v[60:63], v[174:177], v[198:201], v[60:63]
	v_mfma_f32_16x16x32_bf16 v[48:51], v[146:149], v[202:205], v[48:51]
	v_mfma_f32_16x16x32_bf16 v[48:51], v[166:169], v[228:231], v[48:51]
	v_mfma_f32_16x16x32_bf16 v[44:47], v[170:173], v[202:205], v[44:47]
	v_mfma_f32_16x16x32_bf16 v[44:47], v[174:177], v[228:231], v[44:47]
	v_mfma_f32_16x16x32_bf16 v[32:35], v[146:149], v[232:235], v[32:35]
	v_mfma_f32_16x16x32_bf16 v[32:35], v[166:169], v[236:239], v[32:35]
	v_mfma_f32_16x16x32_bf16 v[28:31], v[170:173], v[232:235], v[28:31]
	v_mfma_f32_16x16x32_bf16 v[28:31], v[174:177], v[236:239], v[28:31]
	v_mfma_f32_16x16x32_bf16 v[16:19], v[146:149], v[240:243], v[16:19]
	v_mfma_f32_16x16x32_bf16 v[16:19], v[166:169], v[244:247], v[16:19]
	v_mfma_f32_16x16x32_bf16 v[12:15], v[170:173], v[240:243], v[12:15]
	v_mfma_f32_16x16x32_bf16 v[12:15], v[174:177], v[244:247], v[12:15]
	s_setprio 0
	s_setprio 1
	v_mfma_f32_16x16x32_bf16 v[56:59], v[178:181], v[194:197], v[56:59]
	v_mfma_f32_16x16x32_bf16 v[56:59], v[182:185], v[198:201], v[56:59]
	v_mfma_f32_16x16x32_bf16 v[52:55], v[186:189], v[194:197], v[52:55]
	v_mfma_f32_16x16x32_bf16 v[52:55], v[190:193], v[198:201], v[52:55]
	v_mfma_f32_16x16x32_bf16 v[40:43], v[178:181], v[202:205], v[40:43]
	v_mfma_f32_16x16x32_bf16 v[40:43], v[182:185], v[228:231], v[40:43]
	v_mfma_f32_16x16x32_bf16 v[36:39], v[186:189], v[202:205], v[36:39]
	v_mfma_f32_16x16x32_bf16 v[36:39], v[190:193], v[228:231], v[36:39]
	s_setprio 2
	s_barrier
	v_mfma_f32_16x16x32_bf16 v[24:27], v[178:181], v[232:235], v[24:27]
	v_mfma_f32_16x16x32_bf16 v[24:27], v[182:185], v[236:239], v[24:27]
	v_mfma_f32_16x16x32_bf16 v[20:23], v[186:189], v[232:235], v[20:23]
	v_mfma_f32_16x16x32_bf16 v[20:23], v[190:193], v[236:239], v[20:23]
	v_mfma_f32_16x16x32_bf16 v[6:9], v[178:181], v[240:243], v[6:9]
	v_mfma_f32_16x16x32_bf16 v[6:9], v[182:185], v[244:247], v[6:9]
	v_mfma_f32_16x16x32_bf16 v[2:5], v[186:189], v[240:243], v[2:5]
	v_mfma_f32_16x16x32_bf16 v[2:5], v[190:193], v[244:247], v[2:5]
	s_setprio 0
	s_add_i32 s48, s48, 2
	s_add_u32 s0, s0, 0x100
	s_addc_u32 s1, s1, 0
	s_add_u32 s46, s46, 0x100
	s_addc_u32 s47, s47, 0
	s_cmp_gt_u32 s48, 29
	s_cbranch_scc0 .LBB0_262
	s_and_b64 vcc, exec, s[28:29]
	s_cbranch_vccz .LBB0_265
	s_barrier

.LBB0_986:
	s_add_u32 s4, s0, 0x100
	s_addc_u32 s5, s1, 0
	s_add_i32 s2, 0, 0x10000
	s_cmpk_eq_i32 s49, 0x54
	s_cselect_b32 s11, s41, s5
	s_cselect_b32 s10, s40, s4
	v_add_u32_e32 v148, s2, v10
	s_cselect_b32 s9, s45, s48
	s_cselect_b32 s8, s44, s33
	s_add_i32 s3, 0, 0x14000
	ds_read_b128 v[144:147], v148
	ds_read_b128 v[166:169], v148 offset:1024
	ds_read_b128 v[170:173], v148 offset:2048
	ds_read_b128 v[174:177], v148 offset:3072
	v_add_u32_e32 v148, s3, v10
	ds_read_b128 v[178:181], v148
	ds_read_b128 v[182:185], v148 offset:1024
	ds_read_b128 v[186:189], v148 offset:2048
	ds_read_b128 v[190:193], v148 offset:3072
	v_lshl_add_u64 v[148:149], s[0:1], 0, v[140:141]
	s_add_i32 m0, s15, 0xc000
	ds_read_b128 v[194:197], v161
	ds_read_b128 v[198:201], v161 offset:1024
	ds_read_b128 v[202:205], v161 offset:2048
	ds_read_b128 v[228:231], v161 offset:3072
	ds_read_b128 v[232:235], v161 offset:4096
	ds_read_b128 v[236:239], v161 offset:5120
	ds_read_b128 v[240:243], v161 offset:6144
	ds_read_b128 v[244:247], v161 offset:7168
	global_load_lds_dwordx4 v[148:149], off
	v_lshl_add_u64 v[148:149], s[0:1], 0, v[142:143]
	s_add_i32 m0, s15, 0xe000
	s_nop 0
	global_load_lds_dwordx4 v[148:149], off
	s_waitcnt vmcnt(8)
	s_waitcnt lgkmcnt(0)
	s_barrier
	s_setprio 1
	s_waitcnt lgkmcnt(0)
	v_mfma_f32_16x16x32_bf16 v[128:131], v[144:147], v[194:197], v[128:131]
	v_mfma_f32_16x16x32_bf16 v[128:131], v[166:169], v[198:201], v[128:131]
	v_mfma_f32_16x16x32_bf16 v[124:127], v[170:173], v[194:197], v[124:127]
	v_mfma_f32_16x16x32_bf16 v[124:127], v[174:177], v[198:201], v[124:127]
	v_mfma_f32_16x16x32_bf16 v[112:115], v[144:147], v[202:205], v[112:115]
	v_mfma_f32_16x16x32_bf16 v[112:115], v[166:169], v[228:231], v[112:115]
	v_mfma_f32_16x16x32_bf16 v[108:111], v[170:173], v[202:205], v[108:111]
	v_mfma_f32_16x16x32_bf16 v[108:111], v[174:177], v[228:231], v[108:111]
	v_mfma_f32_16x16x32_bf16 v[96:99], v[144:147], v[232:235], v[96:99]
	v_mfma_f32_16x16x32_bf16 v[96:99], v[166:169], v[236:239], v[96:99]
	v_mfma_f32_16x16x32_bf16 v[92:95], v[170:173], v[232:235], v[92:95]
	v_mfma_f32_16x16x32_bf16 v[92:95], v[174:177], v[236:239], v[92:95]
	v_mfma_f32_16x16x32_bf16 v[80:83], v[144:147], v[240:243], v[80:83]
	v_mfma_f32_16x16x32_bf16 v[80:83], v[166:169], v[244:247], v[80:83]
	v_mfma_f32_16x16x32_bf16 v[76:79], v[170:173], v[240:243], v[76:79]
	v_mfma_f32_16x16x32_bf16 v[76:79], v[174:177], v[244:247], v[76:79]
	s_setprio 0
	s_setprio 1
	v_mfma_f32_16x16x32_bf16 v[120:123], v[178:181], v[194:197], v[120:123]
	v_mfma_f32_16x16x32_bf16 v[120:123], v[182:185], v[198:201], v[120:123]
	v_mfma_f32_16x16x32_bf16 v[116:119], v[186:189], v[194:197], v[116:119]
	v_mfma_f32_16x16x32_bf16 v[116:119], v[190:193], v[198:201], v[116:119]
	v_mfma_f32_16x16x32_bf16 v[104:107], v[178:181], v[202:205], v[104:107]
	v_mfma_f32_16x16x32_bf16 v[104:107], v[182:185], v[228:231], v[104:107]
	v_mfma_f32_16x16x32_bf16 v[100:103], v[186:189], v[202:205], v[100:103]
	v_mfma_f32_16x16x32_bf16 v[100:103], v[190:193], v[228:231], v[100:103]
	s_setprio 2
	s_barrier
	v_mfma_f32_16x16x32_bf16 v[88:91], v[178:181], v[232:235], v[88:91]
	v_mfma_f32_16x16x32_bf16 v[88:91], v[182:185], v[236:239], v[88:91]
	v_mfma_f32_16x16x32_bf16 v[84:87], v[186:189], v[232:235], v[84:87]
	v_mfma_f32_16x16x32_bf16 v[84:87], v[190:193], v[236:239], v[84:87]
	v_mfma_f32_16x16x32_bf16 v[72:75], v[178:181], v[240:243], v[72:75]
	v_mfma_f32_16x16x32_bf16 v[72:75], v[182:185], v[244:247], v[72:75]
	v_mfma_f32_16x16x32_bf16 v[68:71], v[186:189], v[240:243], v[68:71]
	v_mfma_f32_16x16x32_bf16 v[68:71], v[190:193], v[244:247], v[68:71]
	s_setprio 0
	s_add_i32 s0, s2, s14
	v_lshl_add_u64 v[148:149], s[8:9], 0, v[136:137]
	s_mov_b32 m0, s0
	ds_read_b128 v[194:197], v161 offset:16384
	ds_read_b128 v[198:201], v161 offset:17408
	ds_read_b128 v[202:205], v161 offset:18432
	ds_read_b128 v[228:231], v161 offset:19456
	ds_read_b128 v[232:235], v161 offset:20480
	ds_read_b128 v[236:239], v161 offset:21504
	ds_read_b128 v[240:243], v161 offset:22528
	ds_read_b128 v[244:247], v161 offset:23552
	global_load_lds_dwordx4 v[148:149], off
	s_add_i32 m0, s0, 0x2000
	s_add_u32 s0, s8, 0x160000
	v_lshl_add_u64 v[212:213], s[8:9], 0, v[132:133]
	s_addc_u32 s1, s9, 0
	s_add_i32 s2, s3, s14
	global_load_lds_dwordx4 v[212:213], off
	v_lshl_add_u64 v[214:215], s[0:1], 0, v[136:137]
	s_mov_b32 m0, s2
	v_lshl_add_u64 v[216:217], s[10:11], 0, v[134:135]
	global_load_lds_dwordx4 v[214:215], off
	v_lshl_add_u64 v[214:215], s[0:1], 0, v[132:133]
	s_add_i32 m0, s2, 0x2000
	s_nop 0
	global_load_lds_dwordx4 v[214:215], off
	v_lshl_add_u64 v[214:215], s[10:11], 0, v[138:139]
	s_mov_b32 m0, s15
	s_nop 0
	global_load_lds_dwordx4 v[214:215], off
	s_mov_b32 m0, s18
	s_nop 0
	global_load_lds_dwordx4 v[216:217], off
	s_waitcnt vmcnt(8)
	s_waitcnt lgkmcnt(0)
	s_barrier
	s_setprio 1
	s_waitcnt lgkmcnt(0)
	v_mfma_f32_16x16x32_bf16 v[64:67], v[144:147], v[194:197], v[64:67]
	v_mfma_f32_16x16x32_bf16 v[64:67], v[166:169], v[198:201], v[64:67]
	v_mfma_f32_16x16x32_bf16 v[60:63], v[170:173], v[194:197], v[60:63]
	v_mfma_f32_16x16x32_bf16 v[60:63], v[174:177], v[198:201], v[60:63]
	v_mfma_f32_16x16x32_bf16 v[48:51], v[144:147], v[202:205], v[48:51]
	v_mfma_f32_16x16x32_bf16 v[48:51], v[166:169], v[228:231], v[48:51]
	v_mfma_f32_16x16x32_bf16 v[44:47], v[170:173], v[202:205], v[44:47]
	v_mfma_f32_16x16x32_bf16 v[44:47], v[174:177], v[228:231], v[44:47]
	v_mfma_f32_16x16x32_bf16 v[32:35], v[144:147], v[232:235], v[32:35]
	v_mfma_f32_16x16x32_bf16 v[32:35], v[166:169], v[236:239], v[32:35]
	v_mfma_f32_16x16x32_bf16 v[28:31], v[170:173], v[232:235], v[28:31]
	v_mfma_f32_16x16x32_bf16 v[28:31], v[174:177], v[236:239], v[28:31]
	v_mfma_f32_16x16x32_bf16 v[16:19], v[144:147], v[240:243], v[16:19]
	v_mfma_f32_16x16x32_bf16 v[16:19], v[166:169], v[244:247], v[16:19]
	v_mfma_f32_16x16x32_bf16 v[12:15], v[170:173], v[240:243], v[12:15]
	v_mfma_f32_16x16x32_bf16 v[12:15], v[174:177], v[244:247], v[12:15]
	s_setprio 0
	s_setprio 1
	v_mfma_f32_16x16x32_bf16 v[56:59], v[178:181], v[194:197], v[56:59]
	v_mfma_f32_16x16x32_bf16 v[56:59], v[182:185], v[198:201], v[56:59]
	v_mfma_f32_16x16x32_bf16 v[52:55], v[186:189], v[194:197], v[52:55]
	v_mfma_f32_16x16x32_bf16 v[52:55], v[190:193], v[198:201], v[52:55]
	v_mfma_f32_16x16x32_bf16 v[40:43], v[178:181], v[202:205], v[40:43]
	v_mfma_f32_16x16x32_bf16 v[40:43], v[182:185], v[228:231], v[40:43]
	v_mfma_f32_16x16x32_bf16 v[36:39], v[186:189], v[202:205], v[36:39]
	v_mfma_f32_16x16x32_bf16 v[36:39], v[190:193], v[228:231], v[36:39]
	s_setprio 2
	s_barrier
	v_mfma_f32_16x16x32_bf16 v[24:27], v[178:181], v[232:235], v[24:27]
	v_mfma_f32_16x16x32_bf16 v[24:27], v[182:185], v[236:239], v[24:27]
	v_mfma_f32_16x16x32_bf16 v[20:23], v[186:189], v[232:235], v[20:23]
	v_mfma_f32_16x16x32_bf16 v[20:23], v[190:193], v[236:239], v[20:23]
	v_mfma_f32_16x16x32_bf16 v[6:9], v[178:181], v[240:243], v[6:9]
	v_mfma_f32_16x16x32_bf16 v[6:9], v[182:185], v[244:247], v[6:9]
	v_mfma_f32_16x16x32_bf16 v[2:5], v[186:189], v[240:243], v[2:5]
	v_mfma_f32_16x16x32_bf16 v[2:5], v[190:193], v[244:247], v[2:5]
	s_setprio 0
	s_add_i32 s2, 0, 0x18000
	s_add_i32 s3, 0, 0x1c000
	v_add_u32_e32 v174, s2, v10
	v_add_u32_e32 v190, s3, v10
	ds_read_b128 v[144:147], v174
	ds_read_b128 v[166:169], v174 offset:1024
	ds_read_b128 v[170:173], v174 offset:2048
	ds_read_b128 v[174:177], v174 offset:3072
	ds_read_b128 v[178:181], v190
	ds_read_b128 v[182:185], v190 offset:1024
	ds_read_b128 v[186:189], v190 offset:2048
	ds_read_b128 v[190:193], v190 offset:3072
	s_add_u32 s0, s10, 0x160000
	s_addc_u32 s1, s11, 0
	s_mov_b32 m0, s19
	v_lshl_add_u64 v[218:219], s[0:1], 0, v[138:139]
	ds_read_b128 v[194:197], v161 offset:32768
	ds_read_b128 v[198:201], v161 offset:33792
	ds_read_b128 v[202:205], v161 offset:34816
	ds_read_b128 v[228:231], v161 offset:35840
	ds_read_b128 v[232:235], v161 offset:36864
	ds_read_b128 v[236:239], v161 offset:37888
	ds_read_b128 v[240:243], v161 offset:38912
	ds_read_b128 v[244:247], v161 offset:39936
	global_load_lds_dwordx4 v[218:219], off
	v_lshl_add_u64 v[218:219], s[0:1], 0, v[134:135]
	s_mov_b32 m0, s22
	s_nop 0
	global_load_lds_dwordx4 v[218:219], off
	s_waitcnt vmcnt(8)
	s_waitcnt lgkmcnt(0)
	s_barrier
	s_setprio 1
	s_waitcnt lgkmcnt(0)
	v_mfma_f32_16x16x32_bf16 v[128:131], v[144:147], v[194:197], v[128:131]
	v_mfma_f32_16x16x32_bf16 v[128:131], v[166:169], v[198:201], v[128:131]
	v_mfma_f32_16x16x32_bf16 v[124:127], v[170:173], v[194:197], v[124:127]
	v_mfma_f32_16x16x32_bf16 v[124:127], v[174:177], v[198:201], v[124:127]
	v_mfma_f32_16x16x32_bf16 v[112:115], v[144:147], v[202:205], v[112:115]
	v_mfma_f32_16x16x32_bf16 v[112:115], v[166:169], v[228:231], v[112:115]
	v_mfma_f32_16x16x32_bf16 v[108:111], v[170:173], v[202:205], v[108:111]
	v_mfma_f32_16x16x32_bf16 v[108:111], v[174:177], v[228:231], v[108:111]
	v_mfma_f32_16x16x32_bf16 v[96:99], v[144:147], v[232:235], v[96:99]
	v_mfma_f32_16x16x32_bf16 v[96:99], v[166:169], v[236:239], v[96:99]
	v_mfma_f32_16x16x32_bf16 v[92:95], v[170:173], v[232:235], v[92:95]
	v_mfma_f32_16x16x32_bf16 v[92:95], v[174:177], v[236:239], v[92:95]
	v_mfma_f32_16x16x32_bf16 v[80:83], v[144:147], v[240:243], v[80:83]
	v_mfma_f32_16x16x32_bf16 v[80:83], v[166:169], v[244:247], v[80:83]
	v_mfma_f32_16x16x32_bf16 v[76:79], v[170:173], v[240:243], v[76:79]
	v_mfma_f32_16x16x32_bf16 v[76:79], v[174:177], v[244:247], v[76:79]
	s_setprio 0
	s_setprio 1
	v_mfma_f32_16x16x32_bf16 v[120:123], v[178:181], v[194:197], v[120:123]
	v_mfma_f32_16x16x32_bf16 v[120:123], v[182:185], v[198:201], v[120:123]
	v_mfma_f32_16x16x32_bf16 v[116:119], v[186:189], v[194:197], v[116:119]
	v_mfma_f32_16x16x32_bf16 v[116:119], v[190:193], v[198:201], v[116:119]
	v_mfma_f32_16x16x32_bf16 v[104:107], v[178:181], v[202:205], v[104:107]
	v_mfma_f32_16x16x32_bf16 v[104:107], v[182:185], v[228:231], v[104:107]
	v_mfma_f32_16x16x32_bf16 v[100:103], v[186:189], v[202:205], v[100:103]
	v_mfma_f32_16x16x32_bf16 v[100:103], v[190:193], v[228:231], v[100:103]
	s_setprio 2
	s_barrier
	v_mfma_f32_16x16x32_bf16 v[88:91], v[178:181], v[232:235], v[88:91]
	v_mfma_f32_16x16x32_bf16 v[88:91], v[182:185], v[236:239], v[88:91]
	v_mfma_f32_16x16x32_bf16 v[84:87], v[186:189], v[232:235], v[84:87]
	v_mfma_f32_16x16x32_bf16 v[84:87], v[190:193], v[236:239], v[84:87]
	v_mfma_f32_16x16x32_bf16 v[72:75], v[178:181], v[240:243], v[72:75]
	v_mfma_f32_16x16x32_bf16 v[72:75], v[182:185], v[244:247], v[72:75]
	v_mfma_f32_16x16x32_bf16 v[68:71], v[186:189], v[240:243], v[68:71]
	v_mfma_f32_16x16x32_bf16 v[68:71], v[190:193], v[244:247], v[68:71]
	s_setprio 0
	s_add_i32 s0, s2, s14
	v_lshl_add_u64 v[148:149], v[148:149], 0, s[86:87]
	s_mov_b32 m0, s0
	ds_read_b128 v[194:197], v161 offset:49152
	ds_read_b128 v[198:201], v161 offset:50176
	ds_read_b128 v[202:205], v161 offset:51200
	ds_read_b128 v[228:231], v161 offset:52224
	ds_read_b128 v[232:235], v161 offset:53248
	ds_read_b128 v[236:239], v161 offset:54272
	ds_read_b128 v[240:243], v161 offset:55296
	ds_read_b128 v[244:247], v161 offset:56320
	global_load_lds_dwordx4 v[148:149], off
	s_add_i32 m0, s0, 0x2000
	s_add_u32 s0, s8, 0x160080
	v_lshl_add_u64 v[148:149], v[212:213], 0, s[86:87]
	s_addc_u32 s1, s9, 0
	s_add_i32 s2, s3, s14
	global_load_lds_dwordx4 v[148:149], off
	v_lshl_add_u64 v[148:149], s[0:1], 0, v[136:137]
	s_mov_b32 m0, s2
	s_nop 0
	global_load_lds_dwordx4 v[148:149], off
	v_lshl_add_u64 v[148:149], s[0:1], 0, v[132:133]
	s_add_i32 m0, s2, 0x2000
	s_nop 0
	global_load_lds_dwordx4 v[148:149], off
	v_lshl_add_u64 v[148:149], v[214:215], 0, s[86:87]
	s_mov_b32 m0, s31
	s_nop 0
	global_load_lds_dwordx4 v[148:149], off
	v_lshl_add_u64 v[148:149], v[216:217], 0, s[86:87]
	s_mov_b32 m0, s34
	s_nop 0
	global_load_lds_dwordx4 v[148:149], off
	s_waitcnt vmcnt(8)
	s_waitcnt lgkmcnt(0)
	s_barrier
	s_setprio 1
	s_waitcnt lgkmcnt(0)
	v_mfma_f32_16x16x32_bf16 v[64:67], v[144:147], v[194:197], v[64:67]
	v_mfma_f32_16x16x32_bf16 v[64:67], v[166:169], v[198:201], v[64:67]
	v_mfma_f32_16x16x32_bf16 v[60:63], v[170:173], v[194:197], v[60:63]
	v_mfma_f32_16x16x32_bf16 v[60:63], v[174:177], v[198:201], v[60:63]
	v_mfma_f32_16x16x32_bf16 v[48:51], v[144:147], v[202:205], v[48:51]
	v_mfma_f32_16x16x32_bf16 v[48:51], v[166:169], v[228:231], v[48:51]
	v_mfma_f32_16x16x32_bf16 v[44:47], v[170:173], v[202:205], v[44:47]
	v_mfma_f32_16x16x32_bf16 v[44:47], v[174:177], v[228:231], v[44:47]
	v_mfma_f32_16x16x32_bf16 v[32:35], v[144:147], v[232:235], v[32:35]
	v_mfma_f32_16x16x32_bf16 v[32:35], v[166:169], v[236:239], v[32:35]
	v_mfma_f32_16x16x32_bf16 v[28:31], v[170:173], v[232:235], v[28:31]
	v_mfma_f32_16x16x32_bf16 v[28:31], v[174:177], v[236:239], v[28:31]
	v_mfma_f32_16x16x32_bf16 v[16:19], v[144:147], v[240:243], v[16:19]
	v_mfma_f32_16x16x32_bf16 v[16:19], v[166:169], v[244:247], v[16:19]
	v_mfma_f32_16x16x32_bf16 v[12:15], v[170:173], v[240:243], v[12:15]
	v_mfma_f32_16x16x32_bf16 v[12:15], v[174:177], v[244:247], v[12:15]
	s_setprio 0
	s_setprio 1
	v_mfma_f32_16x16x32_bf16 v[56:59], v[178:181], v[194:197], v[56:59]
	v_mfma_f32_16x16x32_bf16 v[56:59], v[182:185], v[198:201], v[56:59]
	v_mfma_f32_16x16x32_bf16 v[52:55], v[186:189], v[194:197], v[52:55]
	v_mfma_f32_16x16x32_bf16 v[52:55], v[190:193], v[198:201], v[52:55]
	v_mfma_f32_16x16x32_bf16 v[40:43], v[178:181], v[202:205], v[40:43]
	v_mfma_f32_16x16x32_bf16 v[40:43], v[182:185], v[228:231], v[40:43]
	v_mfma_f32_16x16x32_bf16 v[36:39], v[186:189], v[202:205], v[36:39]
	v_mfma_f32_16x16x32_bf16 v[36:39], v[190:193], v[228:231], v[36:39]
	s_setprio 2
	s_barrier
	v_mfma_f32_16x16x32_bf16 v[24:27], v[178:181], v[232:235], v[24:27]
	v_mfma_f32_16x16x32_bf16 v[24:27], v[182:185], v[236:239], v[24:27]
	v_mfma_f32_16x16x32_bf16 v[20:23], v[186:189], v[232:235], v[20:23]
	v_mfma_f32_16x16x32_bf16 v[20:23], v[190:193], v[236:239], v[20:23]
	v_mfma_f32_16x16x32_bf16 v[6:9], v[178:181], v[240:243], v[6:9]
	v_mfma_f32_16x16x32_bf16 v[6:9], v[182:185], v[244:247], v[6:9]
	v_mfma_f32_16x16x32_bf16 v[2:5], v[186:189], v[240:243], v[2:5]
	v_mfma_f32_16x16x32_bf16 v[2:5], v[190:193], v[244:247], v[2:5]
	s_setprio 0
	s_add_i32 s49, s49, 2
	s_add_u32 s33, s33, 0x100
	s_addc_u32 s48, s48, 0
	s_cmpk_gt_u32 s49, 0x55
	s_mov_b64 s[0:1], s[4:5]
	s_cbranch_scc0 .LBB0_986
	s_and_b64 vcc, exec, s[42:43]
	s_cbranch_vccz .LBB0_989
	s_barrier

.LBB0_1077:
	s_add_u32 s2, s30, 0xfff80080
	s_addc_u32 s3, s31, -1
	s_add_i32 s6, 0, 0x10000
	s_cmp_eq_u32 s61, 28
	s_cselect_b32 s41, s11, s3
	s_cselect_b32 s40, s19, s2
	v_add_u32_e32 v148, s6, v10
	s_cselect_b32 s35, s9, s60
	s_cselect_b32 s34, s29, s59
	s_add_i32 s7, 0, 0x14000
	ds_read_b128 v[166:169], v148
	ds_read_b128 v[170:173], v148 offset:1024
	ds_read_b128 v[174:177], v148 offset:2048
	ds_read_b128 v[178:181], v148 offset:3072
	v_add_u32_e32 v148, s7, v10
	ds_read_b128 v[182:185], v148
	ds_read_b128 v[186:189], v148 offset:1024
	ds_read_b128 v[190:193], v148 offset:2048
	ds_read_b128 v[194:197], v148 offset:3072
	v_lshl_add_u64 v[148:149], s[30:31], 0, v[144:145]
	s_add_i32 m0, s48, 0xc000
	ds_read_b128 v[198:201], v161
	ds_read_b128 v[202:205], v161 offset:1024
	ds_read_b128 v[228:231], v161 offset:2048
	ds_read_b128 v[232:235], v161 offset:3072
	ds_read_b128 v[236:239], v161 offset:4096
	ds_read_b128 v[240:243], v161 offset:5120
	ds_read_b128 v[244:247], v161 offset:6144
	ds_read_b128 v[212:215], v161 offset:7168
	global_load_lds_dwordx4 v[148:149], off
	v_lshl_add_u64 v[148:149], s[30:31], 0, v[146:147]
	s_add_i32 m0, s48, 0xe000
	s_nop 0
	global_load_lds_dwordx4 v[148:149], off
	s_waitcnt vmcnt(8)
	s_waitcnt lgkmcnt(0)
	s_barrier
	s_setprio 1
	s_waitcnt lgkmcnt(0)
	v_mfma_f32_16x16x32_bf16 v[128:131], v[166:169], v[198:201], v[128:131]
	v_mfma_f32_16x16x32_bf16 v[128:131], v[170:173], v[202:205], v[128:131]
	v_mfma_f32_16x16x32_bf16 v[124:127], v[174:177], v[198:201], v[124:127]
	v_mfma_f32_16x16x32_bf16 v[124:127], v[178:181], v[202:205], v[124:127]
	v_mfma_f32_16x16x32_bf16 v[112:115], v[166:169], v[228:231], v[112:115]
	v_mfma_f32_16x16x32_bf16 v[112:115], v[170:173], v[232:235], v[112:115]
	v_mfma_f32_16x16x32_bf16 v[108:111], v[174:177], v[228:231], v[108:111]
	v_mfma_f32_16x16x32_bf16 v[108:111], v[178:181], v[232:235], v[108:111]
	v_mfma_f32_16x16x32_bf16 v[96:99], v[166:169], v[236:239], v[96:99]
	v_mfma_f32_16x16x32_bf16 v[96:99], v[170:173], v[240:243], v[96:99]
	v_mfma_f32_16x16x32_bf16 v[92:95], v[174:177], v[236:239], v[92:95]
	v_mfma_f32_16x16x32_bf16 v[92:95], v[178:181], v[240:243], v[92:95]
	v_mfma_f32_16x16x32_bf16 v[80:83], v[166:169], v[244:247], v[80:83]
	v_mfma_f32_16x16x32_bf16 v[80:83], v[170:173], v[212:215], v[80:83]
	v_mfma_f32_16x16x32_bf16 v[76:79], v[174:177], v[244:247], v[76:79]
	v_mfma_f32_16x16x32_bf16 v[76:79], v[178:181], v[212:215], v[76:79]
	s_setprio 0
	s_setprio 1
	v_mfma_f32_16x16x32_bf16 v[120:123], v[182:185], v[198:201], v[120:123]
	v_mfma_f32_16x16x32_bf16 v[120:123], v[186:189], v[202:205], v[120:123]
	v_mfma_f32_16x16x32_bf16 v[116:119], v[190:193], v[198:201], v[116:119]
	v_mfma_f32_16x16x32_bf16 v[116:119], v[194:197], v[202:205], v[116:119]
	v_mfma_f32_16x16x32_bf16 v[104:107], v[182:185], v[228:231], v[104:107]
	v_mfma_f32_16x16x32_bf16 v[104:107], v[186:189], v[232:235], v[104:107]
	v_mfma_f32_16x16x32_bf16 v[100:103], v[190:193], v[228:231], v[100:103]
	v_mfma_f32_16x16x32_bf16 v[100:103], v[194:197], v[232:235], v[100:103]
	s_setprio 2
	s_barrier
	v_mfma_f32_16x16x32_bf16 v[88:91], v[182:185], v[236:239], v[88:91]
	v_mfma_f32_16x16x32_bf16 v[88:91], v[186:189], v[240:243], v[88:91]
	v_mfma_f32_16x16x32_bf16 v[84:87], v[190:193], v[236:239], v[84:87]
	v_mfma_f32_16x16x32_bf16 v[84:87], v[194:197], v[240:243], v[84:87]
	v_mfma_f32_16x16x32_bf16 v[72:75], v[182:185], v[244:247], v[72:75]
	v_mfma_f32_16x16x32_bf16 v[72:75], v[186:189], v[212:215], v[72:75]
	v_mfma_f32_16x16x32_bf16 v[68:71], v[190:193], v[244:247], v[68:71]
	v_mfma_f32_16x16x32_bf16 v[68:71], v[194:197], v[212:215], v[68:71]
	s_setprio 0
	s_add_i32 s2, s6, s47
	v_lshl_add_u64 v[148:149], s[34:35], 0, v[134:135]
	s_mov_b32 m0, s2
	ds_read_b128 v[198:201], v161 offset:16384
	ds_read_b128 v[202:205], v161 offset:17408
	ds_read_b128 v[212:215], v161 offset:18432
	ds_read_b128 v[228:231], v161 offset:19456
	ds_read_b128 v[232:235], v161 offset:20480
	ds_read_b128 v[236:239], v161 offset:21504
	ds_read_b128 v[240:243], v161 offset:22528
	ds_read_b128 v[244:247], v161 offset:23552
	global_load_lds_dwordx4 v[148:149], off
	s_add_i32 m0, s2, 0x2000
	s_add_u32 s2, s34, 0x80000
	v_lshl_add_u64 v[216:217], s[34:35], 0, v[138:139]
	s_addc_u32 s3, s35, 0
	s_add_i32 s6, s7, s47
	global_load_lds_dwordx4 v[216:217], off
	v_lshl_add_u64 v[218:219], s[2:3], 0, v[134:135]
	s_mov_b32 m0, s6
	v_lshl_add_u64 v[248:249], s[40:41], 0, v[136:137]
	global_load_lds_dwordx4 v[218:219], off
	v_lshl_add_u64 v[218:219], s[2:3], 0, v[138:139]
	s_add_i32 m0, s6, 0x2000
	s_nop 0
	global_load_lds_dwordx4 v[218:219], off
	v_lshl_add_u64 v[218:219], s[40:41], 0, v[132:133]
	s_mov_b32 m0, s48
	s_nop 0
	global_load_lds_dwordx4 v[218:219], off
	s_mov_b32 m0, s49
	s_nop 0
	global_load_lds_dwordx4 v[248:249], off
	s_waitcnt vmcnt(8)
	s_waitcnt lgkmcnt(0)
	s_barrier
	s_setprio 1
	s_waitcnt lgkmcnt(0)
	v_mfma_f32_16x16x32_bf16 v[64:67], v[166:169], v[198:201], v[64:67]
	v_mfma_f32_16x16x32_bf16 v[64:67], v[170:173], v[202:205], v[64:67]
	v_mfma_f32_16x16x32_bf16 v[60:63], v[174:177], v[198:201], v[60:63]
	v_mfma_f32_16x16x32_bf16 v[60:63], v[178:181], v[202:205], v[60:63]
	v_mfma_f32_16x16x32_bf16 v[48:51], v[166:169], v[212:215], v[48:51]
	v_mfma_f32_16x16x32_bf16 v[48:51], v[170:173], v[228:231], v[48:51]
	v_mfma_f32_16x16x32_bf16 v[44:47], v[174:177], v[212:215], v[44:47]
	v_mfma_f32_16x16x32_bf16 v[44:47], v[178:181], v[228:231], v[44:47]
	v_mfma_f32_16x16x32_bf16 v[32:35], v[166:169], v[232:235], v[32:35]
	v_mfma_f32_16x16x32_bf16 v[32:35], v[170:173], v[236:239], v[32:35]
	v_mfma_f32_16x16x32_bf16 v[28:31], v[174:177], v[232:235], v[28:31]
	v_mfma_f32_16x16x32_bf16 v[28:31], v[178:181], v[236:239], v[28:31]
	v_mfma_f32_16x16x32_bf16 v[16:19], v[166:169], v[240:243], v[16:19]
	v_mfma_f32_16x16x32_bf16 v[16:19], v[170:173], v[244:247], v[16:19]
	v_mfma_f32_16x16x32_bf16 v[12:15], v[174:177], v[240:243], v[12:15]
	v_mfma_f32_16x16x32_bf16 v[12:15], v[178:181], v[244:247], v[12:15]
	s_setprio 0
	s_setprio 1
	v_mfma_f32_16x16x32_bf16 v[56:59], v[182:185], v[198:201], v[56:59]
	v_mfma_f32_16x16x32_bf16 v[56:59], v[186:189], v[202:205], v[56:59]
	v_mfma_f32_16x16x32_bf16 v[52:55], v[190:193], v[198:201], v[52:55]
	v_mfma_f32_16x16x32_bf16 v[52:55], v[194:197], v[202:205], v[52:55]
	v_mfma_f32_16x16x32_bf16 v[40:43], v[182:185], v[212:215], v[40:43]
	v_mfma_f32_16x16x32_bf16 v[40:43], v[186:189], v[228:231], v[40:43]
	v_mfma_f32_16x16x32_bf16 v[36:39], v[190:193], v[212:215], v[36:39]
	v_mfma_f32_16x16x32_bf16 v[36:39], v[194:197], v[228:231], v[36:39]
	s_setprio 2
	s_barrier
	v_mfma_f32_16x16x32_bf16 v[24:27], v[182:185], v[232:235], v[24:27]
	v_mfma_f32_16x16x32_bf16 v[24:27], v[186:189], v[236:239], v[24:27]
	v_mfma_f32_16x16x32_bf16 v[20:23], v[190:193], v[232:235], v[20:23]
	v_mfma_f32_16x16x32_bf16 v[20:23], v[194:197], v[236:239], v[20:23]
	v_mfma_f32_16x16x32_bf16 v[6:9], v[182:185], v[240:243], v[6:9]
	v_mfma_f32_16x16x32_bf16 v[6:9], v[186:189], v[244:247], v[6:9]
	v_mfma_f32_16x16x32_bf16 v[2:5], v[190:193], v[240:243], v[2:5]
	v_mfma_f32_16x16x32_bf16 v[2:5], v[194:197], v[244:247], v[2:5]
	s_setprio 0
	s_add_i32 s6, 0, 0x18000
	s_add_i32 s7, 0, 0x1c000
	v_add_u32_e32 v178, s6, v10
	v_add_u32_e32 v194, s7, v10
	ds_read_b128 v[166:169], v178
	ds_read_b128 v[170:173], v178 offset:1024
	ds_read_b128 v[174:177], v178 offset:2048
	ds_read_b128 v[178:181], v178 offset:3072
	ds_read_b128 v[182:185], v194
	ds_read_b128 v[186:189], v194 offset:1024
	ds_read_b128 v[190:193], v194 offset:2048
	ds_read_b128 v[194:197], v194 offset:3072
	s_add_u32 s2, s40, 0x80000
	s_addc_u32 s3, s41, 0
	s_mov_b32 m0, s50
	v_lshl_add_u64 v[220:221], s[2:3], 0, v[132:133]
	ds_read_b128 v[198:201], v161 offset:32768
	ds_read_b128 v[202:205], v161 offset:33792
	ds_read_b128 v[212:215], v161 offset:34816
	ds_read_b128 v[228:231], v161 offset:35840
	ds_read_b128 v[232:235], v161 offset:36864
	ds_read_b128 v[236:239], v161 offset:37888
	ds_read_b128 v[240:243], v161 offset:38912
	ds_read_b128 v[244:247], v161 offset:39936
	global_load_lds_dwordx4 v[220:221], off
	v_lshl_add_u64 v[220:221], s[2:3], 0, v[136:137]
	s_mov_b32 m0, s51
	s_nop 0
	global_load_lds_dwordx4 v[220:221], off
	s_waitcnt vmcnt(8)
	s_waitcnt lgkmcnt(0)
	s_barrier
	s_setprio 1
	s_waitcnt lgkmcnt(0)
	v_mfma_f32_16x16x32_bf16 v[128:131], v[166:169], v[198:201], v[128:131]
	v_mfma_f32_16x16x32_bf16 v[128:131], v[170:173], v[202:205], v[128:131]
	v_mfma_f32_16x16x32_bf16 v[124:127], v[174:177], v[198:201], v[124:127]
	v_mfma_f32_16x16x32_bf16 v[124:127], v[178:181], v[202:205], v[124:127]
	v_mfma_f32_16x16x32_bf16 v[112:115], v[166:169], v[212:215], v[112:115]
	v_mfma_f32_16x16x32_bf16 v[112:115], v[170:173], v[228:231], v[112:115]
	v_mfma_f32_16x16x32_bf16 v[108:111], v[174:177], v[212:215], v[108:111]
	v_mfma_f32_16x16x32_bf16 v[108:111], v[178:181], v[228:231], v[108:111]
	v_mfma_f32_16x16x32_bf16 v[96:99], v[166:169], v[232:235], v[96:99]
	v_mfma_f32_16x16x32_bf16 v[96:99], v[170:173], v[236:239], v[96:99]
	v_mfma_f32_16x16x32_bf16 v[92:95], v[174:177], v[232:235], v[92:95]
	v_mfma_f32_16x16x32_bf16 v[92:95], v[178:181], v[236:239], v[92:95]
	v_mfma_f32_16x16x32_bf16 v[80:83], v[166:169], v[240:243], v[80:83]
	v_mfma_f32_16x16x32_bf16 v[80:83], v[170:173], v[244:247], v[80:83]
	v_mfma_f32_16x16x32_bf16 v[76:79], v[174:177], v[240:243], v[76:79]
	v_mfma_f32_16x16x32_bf16 v[76:79], v[178:181], v[244:247], v[76:79]
	s_setprio 0
	s_setprio 1
	v_mfma_f32_16x16x32_bf16 v[120:123], v[182:185], v[198:201], v[120:123]
	v_mfma_f32_16x16x32_bf16 v[120:123], v[186:189], v[202:205], v[120:123]
	v_mfma_f32_16x16x32_bf16 v[116:119], v[190:193], v[198:201], v[116:119]
	v_mfma_f32_16x16x32_bf16 v[116:119], v[194:197], v[202:205], v[116:119]
	v_mfma_f32_16x16x32_bf16 v[104:107], v[182:185], v[212:215], v[104:107]
	v_mfma_f32_16x16x32_bf16 v[104:107], v[186:189], v[228:231], v[104:107]
	v_mfma_f32_16x16x32_bf16 v[100:103], v[190:193], v[212:215], v[100:103]
	v_mfma_f32_16x16x32_bf16 v[100:103], v[194:197], v[228:231], v[100:103]
	s_setprio 2
	s_barrier
	v_mfma_f32_16x16x32_bf16 v[88:91], v[182:185], v[232:235], v[88:91]
	v_mfma_f32_16x16x32_bf16 v[88:91], v[186:189], v[236:239], v[88:91]
	v_mfma_f32_16x16x32_bf16 v[84:87], v[190:193], v[232:235], v[84:87]
	v_mfma_f32_16x16x32_bf16 v[84:87], v[194:197], v[236:239], v[84:87]
	v_mfma_f32_16x16x32_bf16 v[72:75], v[182:185], v[240:243], v[72:75]
	v_mfma_f32_16x16x32_bf16 v[72:75], v[186:189], v[244:247], v[72:75]
	v_mfma_f32_16x16x32_bf16 v[68:71], v[190:193], v[240:243], v[68:71]
	v_mfma_f32_16x16x32_bf16 v[68:71], v[194:197], v[244:247], v[68:71]
	s_setprio 0
	s_add_i32 s2, s6, s47
	v_lshl_add_u64 v[148:149], v[148:149], 0, s[86:87]
	s_mov_b32 m0, s2
	ds_read_b128 v[198:201], v161 offset:49152
	ds_read_b128 v[202:205], v161 offset:50176
	ds_read_b128 v[212:215], v161 offset:51200
	ds_read_b128 v[228:231], v161 offset:52224
	ds_read_b128 v[232:235], v161 offset:53248
	ds_read_b128 v[236:239], v161 offset:54272
	ds_read_b128 v[240:243], v161 offset:55296
	ds_read_b128 v[244:247], v161 offset:56320
	global_load_lds_dwordx4 v[148:149], off
	s_add_i32 m0, s2, 0x2000
	s_add_u32 s2, s34, 0x80080
	v_lshl_add_u64 v[148:149], v[216:217], 0, s[86:87]
	s_addc_u32 s3, s35, 0
	s_add_i32 s6, s7, s47
	global_load_lds_dwordx4 v[148:149], off
	v_lshl_add_u64 v[148:149], s[2:3], 0, v[134:135]
	s_mov_b32 m0, s6
	s_nop 0
	global_load_lds_dwordx4 v[148:149], off
	v_lshl_add_u64 v[148:149], s[2:3], 0, v[138:139]
	s_add_i32 m0, s6, 0x2000
	s_nop 0
	global_load_lds_dwordx4 v[148:149], off
	v_lshl_add_u64 v[148:149], v[218:219], 0, s[86:87]
	s_mov_b32 m0, s53
	s_nop 0
	global_load_lds_dwordx4 v[148:149], off
	v_lshl_add_u64 v[148:149], v[248:249], 0, s[86:87]
	s_mov_b32 m0, s54
	s_nop 0
	global_load_lds_dwordx4 v[148:149], off
	s_waitcnt vmcnt(8)
	s_waitcnt lgkmcnt(0)
	s_barrier
	s_setprio 1
	s_waitcnt lgkmcnt(0)
	v_mfma_f32_16x16x32_bf16 v[64:67], v[166:169], v[198:201], v[64:67]
	v_mfma_f32_16x16x32_bf16 v[64:67], v[170:173], v[202:205], v[64:67]
	v_mfma_f32_16x16x32_bf16 v[60:63], v[174:177], v[198:201], v[60:63]
	v_mfma_f32_16x16x32_bf16 v[60:63], v[178:181], v[202:205], v[60:63]
	v_mfma_f32_16x16x32_bf16 v[48:51], v[166:169], v[212:215], v[48:51]
	v_mfma_f32_16x16x32_bf16 v[48:51], v[170:173], v[228:231], v[48:51]
	v_mfma_f32_16x16x32_bf16 v[44:47], v[174:177], v[212:215], v[44:47]
	v_mfma_f32_16x16x32_bf16 v[44:47], v[178:181], v[228:231], v[44:47]
	v_mfma_f32_16x16x32_bf16 v[32:35], v[166:169], v[232:235], v[32:35]
	v_mfma_f32_16x16x32_bf16 v[32:35], v[170:173], v[236:239], v[32:35]
	v_mfma_f32_16x16x32_bf16 v[28:31], v[174:177], v[232:235], v[28:31]
	v_mfma_f32_16x16x32_bf16 v[28:31], v[178:181], v[236:239], v[28:31]
	v_mfma_f32_16x16x32_bf16 v[16:19], v[166:169], v[240:243], v[16:19]
	v_mfma_f32_16x16x32_bf16 v[16:19], v[170:173], v[244:247], v[16:19]
	v_mfma_f32_16x16x32_bf16 v[12:15], v[174:177], v[240:243], v[12:15]
	v_mfma_f32_16x16x32_bf16 v[12:15], v[178:181], v[244:247], v[12:15]
	s_setprio 0
	s_setprio 1
	v_mfma_f32_16x16x32_bf16 v[56:59], v[182:185], v[198:201], v[56:59]
	v_mfma_f32_16x16x32_bf16 v[56:59], v[186:189], v[202:205], v[56:59]
	v_mfma_f32_16x16x32_bf16 v[52:55], v[190:193], v[198:201], v[52:55]
	v_mfma_f32_16x16x32_bf16 v[52:55], v[194:197], v[202:205], v[52:55]
	v_mfma_f32_16x16x32_bf16 v[40:43], v[182:185], v[212:215], v[40:43]
	v_mfma_f32_16x16x32_bf16 v[40:43], v[186:189], v[228:231], v[40:43]
	v_mfma_f32_16x16x32_bf16 v[36:39], v[190:193], v[212:215], v[36:39]
	v_mfma_f32_16x16x32_bf16 v[36:39], v[194:197], v[228:231], v[36:39]
	s_setprio 2
	s_barrier
	v_mfma_f32_16x16x32_bf16 v[24:27], v[182:185], v[232:235], v[24:27]
	v_mfma_f32_16x16x32_bf16 v[24:27], v[186:189], v[236:239], v[24:27]
	v_mfma_f32_16x16x32_bf16 v[20:23], v[190:193], v[232:235], v[20:23]
	v_mfma_f32_16x16x32_bf16 v[20:23], v[194:197], v[236:239], v[20:23]
	v_mfma_f32_16x16x32_bf16 v[6:9], v[182:185], v[240:243], v[6:9]
	v_mfma_f32_16x16x32_bf16 v[6:9], v[186:189], v[244:247], v[6:9]
	v_mfma_f32_16x16x32_bf16 v[2:5], v[190:193], v[240:243], v[2:5]
	v_mfma_f32_16x16x32_bf16 v[2:5], v[194:197], v[244:247], v[2:5]
	s_setprio 0
	s_add_i32 s61, s61, 2
	s_add_u32 s30, s30, 0x100
	s_addc_u32 s31, s31, 0
	s_add_u32 s59, s59, 0x100
	s_addc_u32 s60, s60, 0
	s_cmp_gt_u32 s61, 29
	s_cbranch_scc0 .LBB0_1077
	s_and_b64 vcc, exec, s[4:5]
	s_cbranch_vccz .LBB0_1080
	s_barrier

.LBB0_2857:
	s_add_i32 s58, s2, 2
	s_add_u32 s3, s0, 0x80
	s_addc_u32 s4, s1, 0
	s_add_i32 s6, 0, 0x10000
	s_cmp_eq_u32 s55, s2
	s_cselect_b32 s5, s8, s4
	s_cselect_b32 s4, s9, s3
	v_add_u32_e32 v148, s6, v10
	s_cselect_b32 s3, s33, s49
	s_cselect_b32 s2, s41, s47
	s_add_i32 s7, 0, 0x14000
	ds_read_b128 v[144:147], v148
	ds_read_b128 v[166:169], v148 offset:1024
	ds_read_b128 v[170:173], v148 offset:2048
	ds_read_b128 v[174:177], v148 offset:3072
	v_add_u32_e32 v148, s7, v10
	ds_read_b128 v[178:181], v148
	ds_read_b128 v[182:185], v148 offset:1024
	ds_read_b128 v[186:189], v148 offset:2048
	ds_read_b128 v[190:193], v148 offset:3072
	v_lshl_add_u64 v[148:149], s[0:1], 0, v[140:141]
	s_add_i32 m0, s28, 0xc000
	ds_read_b128 v[194:197], v161
	ds_read_b128 v[198:201], v161 offset:1024
	ds_read_b128 v[202:205], v161 offset:2048
	ds_read_b128 v[212:215], v161 offset:3072
	ds_read_b128 v[228:231], v161 offset:4096
	ds_read_b128 v[232:235], v161 offset:5120
	ds_read_b128 v[236:239], v161 offset:6144
	ds_read_b128 v[240:243], v161 offset:7168
	global_load_lds_dwordx4 v[148:149], off
	v_lshl_add_u64 v[148:149], s[0:1], 0, v[142:143]
	s_add_i32 m0, s28, 0xe000
	s_nop 0
	global_load_lds_dwordx4 v[148:149], off
	s_waitcnt vmcnt(8)
	s_waitcnt lgkmcnt(0)
	s_barrier
	s_setprio 1
	s_waitcnt lgkmcnt(0)
	v_mfma_f32_16x16x32_bf16 v[128:131], v[144:147], v[194:197], v[128:131]
	v_mfma_f32_16x16x32_bf16 v[128:131], v[166:169], v[198:201], v[128:131]
	v_mfma_f32_16x16x32_bf16 v[124:127], v[170:173], v[194:197], v[124:127]
	v_mfma_f32_16x16x32_bf16 v[124:127], v[174:177], v[198:201], v[124:127]
	v_mfma_f32_16x16x32_bf16 v[112:115], v[144:147], v[202:205], v[112:115]
	v_mfma_f32_16x16x32_bf16 v[112:115], v[166:169], v[212:215], v[112:115]
	v_mfma_f32_16x16x32_bf16 v[108:111], v[170:173], v[202:205], v[108:111]
	v_mfma_f32_16x16x32_bf16 v[108:111], v[174:177], v[212:215], v[108:111]
	v_mfma_f32_16x16x32_bf16 v[96:99], v[144:147], v[228:231], v[96:99]
	v_mfma_f32_16x16x32_bf16 v[96:99], v[166:169], v[232:235], v[96:99]
	v_mfma_f32_16x16x32_bf16 v[92:95], v[170:173], v[228:231], v[92:95]
	v_mfma_f32_16x16x32_bf16 v[92:95], v[174:177], v[232:235], v[92:95]
	v_mfma_f32_16x16x32_bf16 v[80:83], v[144:147], v[236:239], v[80:83]
	v_mfma_f32_16x16x32_bf16 v[80:83], v[166:169], v[240:243], v[80:83]
	v_mfma_f32_16x16x32_bf16 v[76:79], v[170:173], v[236:239], v[76:79]
	v_mfma_f32_16x16x32_bf16 v[76:79], v[174:177], v[240:243], v[76:79]
	s_setprio 0
	s_setprio 1
	v_mfma_f32_16x16x32_bf16 v[120:123], v[178:181], v[194:197], v[120:123]
	v_mfma_f32_16x16x32_bf16 v[120:123], v[182:185], v[198:201], v[120:123]
	v_mfma_f32_16x16x32_bf16 v[116:119], v[186:189], v[194:197], v[116:119]
	v_mfma_f32_16x16x32_bf16 v[116:119], v[190:193], v[198:201], v[116:119]
	v_mfma_f32_16x16x32_bf16 v[104:107], v[178:181], v[202:205], v[104:107]
	v_mfma_f32_16x16x32_bf16 v[104:107], v[182:185], v[212:215], v[104:107]
	v_mfma_f32_16x16x32_bf16 v[100:103], v[186:189], v[202:205], v[100:103]
	v_mfma_f32_16x16x32_bf16 v[100:103], v[190:193], v[212:215], v[100:103]
	s_setprio 2
	s_barrier
	v_mfma_f32_16x16x32_bf16 v[88:91], v[178:181], v[228:231], v[88:91]
	v_mfma_f32_16x16x32_bf16 v[88:91], v[182:185], v[232:235], v[88:91]
	v_mfma_f32_16x16x32_bf16 v[84:87], v[186:189], v[228:231], v[84:87]
	v_mfma_f32_16x16x32_bf16 v[84:87], v[190:193], v[232:235], v[84:87]
	v_mfma_f32_16x16x32_bf16 v[72:75], v[178:181], v[236:239], v[72:75]
	v_mfma_f32_16x16x32_bf16 v[72:75], v[182:185], v[240:243], v[72:75]
	v_mfma_f32_16x16x32_bf16 v[68:71], v[186:189], v[236:239], v[68:71]
	v_mfma_f32_16x16x32_bf16 v[68:71], v[190:193], v[240:243], v[68:71]
	s_setprio 0
	s_add_i32 s6, s6, s22
	v_lshl_add_u64 v[148:149], s[2:3], 0, v[136:137]
	s_mov_b32 m0, s6
	ds_read_b128 v[194:197], v161 offset:16384
	ds_read_b128 v[198:201], v161 offset:17408
	ds_read_b128 v[202:205], v161 offset:18432
	ds_read_b128 v[212:215], v161 offset:19456
	ds_read_b128 v[228:231], v161 offset:20480
	ds_read_b128 v[232:235], v161 offset:21504
	ds_read_b128 v[236:239], v161 offset:22528
	ds_read_b128 v[240:243], v161 offset:23552
	global_load_lds_dwordx4 v[148:149], off
	s_add_i32 m0, s6, 0x2000
	v_lshl_add_u64 v[216:217], s[2:3], 0, v[132:133]
	s_add_u32 s2, s2, s40
	s_addc_u32 s3, s3, 0
	s_add_i32 s6, s7, s22
	global_load_lds_dwordx4 v[216:217], off
	v_lshl_add_u64 v[218:219], s[2:3], 0, v[136:137]
	s_mov_b32 m0, s6
	v_lshl_add_u64 v[220:221], s[2:3], 0, v[132:133]
	global_load_lds_dwordx4 v[218:219], off
	s_add_i32 m0, s6, 0x2000
	v_lshl_add_u64 v[244:245], s[4:5], 0, v[138:139]
	global_load_lds_dwordx4 v[220:221], off
	s_mov_b32 m0, s28
	v_lshl_add_u64 v[246:247], s[4:5], 0, v[134:135]
	global_load_lds_dwordx4 v[244:245], off
	s_mov_b32 m0, s29
	s_nop 0
	global_load_lds_dwordx4 v[246:247], off
	s_waitcnt vmcnt(8)
	s_waitcnt lgkmcnt(0)
	s_barrier
	s_setprio 1
	s_waitcnt lgkmcnt(0)
	v_mfma_f32_16x16x32_bf16 v[64:67], v[144:147], v[194:197], v[64:67]
	v_mfma_f32_16x16x32_bf16 v[64:67], v[166:169], v[198:201], v[64:67]
	v_mfma_f32_16x16x32_bf16 v[60:63], v[170:173], v[194:197], v[60:63]
	v_mfma_f32_16x16x32_bf16 v[60:63], v[174:177], v[198:201], v[60:63]
	v_mfma_f32_16x16x32_bf16 v[48:51], v[144:147], v[202:205], v[48:51]
	v_mfma_f32_16x16x32_bf16 v[48:51], v[166:169], v[212:215], v[48:51]
	v_mfma_f32_16x16x32_bf16 v[44:47], v[170:173], v[202:205], v[44:47]
	v_mfma_f32_16x16x32_bf16 v[44:47], v[174:177], v[212:215], v[44:47]
	v_mfma_f32_16x16x32_bf16 v[32:35], v[144:147], v[228:231], v[32:35]
	v_mfma_f32_16x16x32_bf16 v[32:35], v[166:169], v[232:235], v[32:35]
	v_mfma_f32_16x16x32_bf16 v[28:31], v[170:173], v[228:231], v[28:31]
	v_mfma_f32_16x16x32_bf16 v[28:31], v[174:177], v[232:235], v[28:31]
	v_mfma_f32_16x16x32_bf16 v[16:19], v[144:147], v[236:239], v[16:19]
	v_mfma_f32_16x16x32_bf16 v[16:19], v[166:169], v[240:243], v[16:19]
	v_mfma_f32_16x16x32_bf16 v[12:15], v[170:173], v[236:239], v[12:15]
	v_mfma_f32_16x16x32_bf16 v[12:15], v[174:177], v[240:243], v[12:15]
	s_setprio 0
	s_setprio 1
	v_mfma_f32_16x16x32_bf16 v[56:59], v[178:181], v[194:197], v[56:59]
	v_mfma_f32_16x16x32_bf16 v[56:59], v[182:185], v[198:201], v[56:59]
	v_mfma_f32_16x16x32_bf16 v[52:55], v[186:189], v[194:197], v[52:55]
	v_mfma_f32_16x16x32_bf16 v[52:55], v[190:193], v[198:201], v[52:55]
	v_mfma_f32_16x16x32_bf16 v[40:43], v[178:181], v[202:205], v[40:43]
	v_mfma_f32_16x16x32_bf16 v[40:43], v[182:185], v[212:215], v[40:43]
	v_mfma_f32_16x16x32_bf16 v[36:39], v[186:189], v[202:205], v[36:39]
	v_mfma_f32_16x16x32_bf16 v[36:39], v[190:193], v[212:215], v[36:39]
	s_setprio 2
	s_barrier
	v_mfma_f32_16x16x32_bf16 v[24:27], v[178:181], v[228:231], v[24:27]
	v_mfma_f32_16x16x32_bf16 v[24:27], v[182:185], v[232:235], v[24:27]
	v_mfma_f32_16x16x32_bf16 v[20:23], v[186:189], v[228:231], v[20:23]
	v_mfma_f32_16x16x32_bf16 v[20:23], v[190:193], v[232:235], v[20:23]
	v_mfma_f32_16x16x32_bf16 v[6:9], v[178:181], v[236:239], v[6:9]
	v_mfma_f32_16x16x32_bf16 v[6:9], v[182:185], v[240:243], v[6:9]
	v_mfma_f32_16x16x32_bf16 v[2:5], v[186:189], v[236:239], v[2:5]
	v_mfma_f32_16x16x32_bf16 v[2:5], v[190:193], v[240:243], v[2:5]
	s_setprio 0
	s_add_i32 s6, 0, 0x18000
	s_add_i32 s7, 0, 0x1c000
	v_add_u32_e32 v174, s6, v10
	v_add_u32_e32 v190, s7, v10
	ds_read_b128 v[144:147], v174
	ds_read_b128 v[166:169], v174 offset:1024
	ds_read_b128 v[170:173], v174 offset:2048
	ds_read_b128 v[174:177], v174 offset:3072
	ds_read_b128 v[178:181], v190
	ds_read_b128 v[182:185], v190 offset:1024
	ds_read_b128 v[186:189], v190 offset:2048
	ds_read_b128 v[190:193], v190 offset:3072
	s_add_u32 s2, s4, s40
	s_addc_u32 s3, s5, 0
	s_mov_b32 m0, s30
	v_lshl_add_u64 v[248:249], s[2:3], 0, v[138:139]
	ds_read_b128 v[194:197], v161 offset:32768
	ds_read_b128 v[198:201], v161 offset:33792
	ds_read_b128 v[202:205], v161 offset:34816
	ds_read_b128 v[212:215], v161 offset:35840
	ds_read_b128 v[228:231], v161 offset:36864
	ds_read_b128 v[232:235], v161 offset:37888
	ds_read_b128 v[236:239], v161 offset:38912
	ds_read_b128 v[240:243], v161 offset:39936
	global_load_lds_dwordx4 v[248:249], off
	v_lshl_add_u64 v[248:249], s[2:3], 0, v[134:135]
	s_mov_b32 m0, s31
	s_nop 0
	global_load_lds_dwordx4 v[248:249], off
	s_waitcnt vmcnt(8)
	s_waitcnt lgkmcnt(0)
	s_barrier
	s_setprio 1
	s_waitcnt lgkmcnt(0)
	v_mfma_f32_16x16x32_bf16 v[128:131], v[144:147], v[194:197], v[128:131]
	v_mfma_f32_16x16x32_bf16 v[128:131], v[166:169], v[198:201], v[128:131]
	v_mfma_f32_16x16x32_bf16 v[124:127], v[170:173], v[194:197], v[124:127]
	v_mfma_f32_16x16x32_bf16 v[124:127], v[174:177], v[198:201], v[124:127]
	v_mfma_f32_16x16x32_bf16 v[112:115], v[144:147], v[202:205], v[112:115]
	v_mfma_f32_16x16x32_bf16 v[112:115], v[166:169], v[212:215], v[112:115]
	v_mfma_f32_16x16x32_bf16 v[108:111], v[170:173], v[202:205], v[108:111]
	v_mfma_f32_16x16x32_bf16 v[108:111], v[174:177], v[212:215], v[108:111]
	v_mfma_f32_16x16x32_bf16 v[96:99], v[144:147], v[228:231], v[96:99]
	v_mfma_f32_16x16x32_bf16 v[96:99], v[166:169], v[232:235], v[96:99]
	v_mfma_f32_16x16x32_bf16 v[92:95], v[170:173], v[228:231], v[92:95]
	v_mfma_f32_16x16x32_bf16 v[92:95], v[174:177], v[232:235], v[92:95]
	v_mfma_f32_16x16x32_bf16 v[80:83], v[144:147], v[236:239], v[80:83]
	v_mfma_f32_16x16x32_bf16 v[80:83], v[166:169], v[240:243], v[80:83]
	v_mfma_f32_16x16x32_bf16 v[76:79], v[170:173], v[236:239], v[76:79]
	v_mfma_f32_16x16x32_bf16 v[76:79], v[174:177], v[240:243], v[76:79]
	s_setprio 0
	s_setprio 1
	v_mfma_f32_16x16x32_bf16 v[120:123], v[178:181], v[194:197], v[120:123]
	v_mfma_f32_16x16x32_bf16 v[120:123], v[182:185], v[198:201], v[120:123]
	v_mfma_f32_16x16x32_bf16 v[116:119], v[186:189], v[194:197], v[116:119]
	v_mfma_f32_16x16x32_bf16 v[116:119], v[190:193], v[198:201], v[116:119]
	v_mfma_f32_16x16x32_bf16 v[104:107], v[178:181], v[202:205], v[104:107]
	v_mfma_f32_16x16x32_bf16 v[104:107], v[182:185], v[212:215], v[104:107]
	v_mfma_f32_16x16x32_bf16 v[100:103], v[186:189], v[202:205], v[100:103]
	v_mfma_f32_16x16x32_bf16 v[100:103], v[190:193], v[212:215], v[100:103]
	s_setprio 2
	s_barrier
	v_mfma_f32_16x16x32_bf16 v[88:91], v[178:181], v[228:231], v[88:91]
	v_mfma_f32_16x16x32_bf16 v[88:91], v[182:185], v[232:235], v[88:91]
	v_mfma_f32_16x16x32_bf16 v[84:87], v[186:189], v[228:231], v[84:87]
	v_mfma_f32_16x16x32_bf16 v[84:87], v[190:193], v[232:235], v[84:87]
	v_mfma_f32_16x16x32_bf16 v[72:75], v[178:181], v[236:239], v[72:75]
	v_mfma_f32_16x16x32_bf16 v[72:75], v[182:185], v[240:243], v[72:75]
	v_mfma_f32_16x16x32_bf16 v[68:71], v[186:189], v[236:239], v[68:71]
	v_mfma_f32_16x16x32_bf16 v[68:71], v[190:193], v[240:243], v[68:71]
	s_setprio 0
	s_add_i32 s2, s6, s22
	v_lshl_add_u64 v[148:149], v[148:149], 0, s[86:87]
	s_mov_b32 m0, s2
	ds_read_b128 v[194:197], v161 offset:49152
	ds_read_b128 v[198:201], v161 offset:50176
	ds_read_b128 v[202:205], v161 offset:51200
	ds_read_b128 v[212:215], v161 offset:52224
	ds_read_b128 v[228:231], v161 offset:53248
	ds_read_b128 v[232:235], v161 offset:54272
	ds_read_b128 v[236:239], v161 offset:55296
	ds_read_b128 v[240:243], v161 offset:56320
	global_load_lds_dwordx4 v[148:149], off
	v_lshl_add_u64 v[148:149], v[216:217], 0, s[86:87]
	s_add_i32 m0, s2, 0x2000
	s_add_i32 s2, s7, s22
	global_load_lds_dwordx4 v[148:149], off
	v_lshl_add_u64 v[148:149], v[218:219], 0, s[86:87]
	s_mov_b32 m0, s2
	s_nop 0
	global_load_lds_dwordx4 v[148:149], off
	v_lshl_add_u64 v[148:149], v[220:221], 0, s[86:87]
	s_add_i32 m0, s2, 0x2000
	s_nop 0
	global_load_lds_dwordx4 v[148:149], off
	v_lshl_add_u64 v[148:149], v[244:245], 0, s[86:87]
	s_mov_b32 m0, s34
	s_nop 0
	global_load_lds_dwordx4 v[148:149], off
	v_lshl_add_u64 v[148:149], v[246:247], 0, s[86:87]
	s_mov_b32 m0, s35
	s_nop 0
	global_load_lds_dwordx4 v[148:149], off
	s_waitcnt vmcnt(8)
	s_waitcnt lgkmcnt(0)
	s_barrier
	s_setprio 1
	s_waitcnt lgkmcnt(0)
	v_mfma_f32_16x16x32_bf16 v[64:67], v[144:147], v[194:197], v[64:67]
	v_mfma_f32_16x16x32_bf16 v[64:67], v[166:169], v[198:201], v[64:67]
	v_mfma_f32_16x16x32_bf16 v[60:63], v[170:173], v[194:197], v[60:63]
	v_mfma_f32_16x16x32_bf16 v[60:63], v[174:177], v[198:201], v[60:63]
	v_mfma_f32_16x16x32_bf16 v[48:51], v[144:147], v[202:205], v[48:51]
	v_mfma_f32_16x16x32_bf16 v[48:51], v[166:169], v[212:215], v[48:51]
	v_mfma_f32_16x16x32_bf16 v[44:47], v[170:173], v[202:205], v[44:47]
	v_mfma_f32_16x16x32_bf16 v[44:47], v[174:177], v[212:215], v[44:47]
	v_mfma_f32_16x16x32_bf16 v[32:35], v[144:147], v[228:231], v[32:35]
	v_mfma_f32_16x16x32_bf16 v[32:35], v[166:169], v[232:235], v[32:35]
	v_mfma_f32_16x16x32_bf16 v[28:31], v[170:173], v[228:231], v[28:31]
	v_mfma_f32_16x16x32_bf16 v[28:31], v[174:177], v[232:235], v[28:31]
	v_mfma_f32_16x16x32_bf16 v[16:19], v[144:147], v[236:239], v[16:19]
	v_mfma_f32_16x16x32_bf16 v[16:19], v[166:169], v[240:243], v[16:19]
	v_mfma_f32_16x16x32_bf16 v[12:15], v[170:173], v[236:239], v[12:15]
	v_mfma_f32_16x16x32_bf16 v[12:15], v[174:177], v[240:243], v[12:15]
	s_setprio 0
	s_setprio 1
	v_mfma_f32_16x16x32_bf16 v[56:59], v[178:181], v[194:197], v[56:59]
	v_mfma_f32_16x16x32_bf16 v[56:59], v[182:185], v[198:201], v[56:59]
	v_mfma_f32_16x16x32_bf16 v[52:55], v[186:189], v[194:197], v[52:55]
	v_mfma_f32_16x16x32_bf16 v[52:55], v[190:193], v[198:201], v[52:55]
	v_mfma_f32_16x16x32_bf16 v[40:43], v[178:181], v[202:205], v[40:43]
	v_mfma_f32_16x16x32_bf16 v[40:43], v[182:185], v[212:215], v[40:43]
	v_mfma_f32_16x16x32_bf16 v[36:39], v[186:189], v[202:205], v[36:39]
	v_mfma_f32_16x16x32_bf16 v[36:39], v[190:193], v[212:215], v[36:39]
	s_setprio 2
	s_barrier
	v_mfma_f32_16x16x32_bf16 v[24:27], v[178:181], v[228:231], v[24:27]
	v_mfma_f32_16x16x32_bf16 v[24:27], v[182:185], v[232:235], v[24:27]
	v_mfma_f32_16x16x32_bf16 v[20:23], v[186:189], v[228:231], v[20:23]
	v_mfma_f32_16x16x32_bf16 v[20:23], v[190:193], v[232:235], v[20:23]
	v_mfma_f32_16x16x32_bf16 v[6:9], v[178:181], v[236:239], v[6:9]
	v_mfma_f32_16x16x32_bf16 v[6:9], v[182:185], v[240:243], v[6:9]
	v_mfma_f32_16x16x32_bf16 v[2:5], v[186:189], v[236:239], v[2:5]
	v_mfma_f32_16x16x32_bf16 v[2:5], v[190:193], v[240:243], v[2:5]
	s_setprio 0
	s_add_u32 s0, s0, 0x100
	s_addc_u32 s1, s1, 0
	s_add_u32 s47, s47, 0x100
	s_addc_u32 s49, s49, 0
	s_cmp_ge_u32 s58, s54
	s_mov_b32 s2, s58
	s_cbranch_scc0 .LBB0_2857
	s_and_b64 vcc, exec, s[44:45]
	s_cbranch_vccz .LBB0_2860
	s_barrier
